# v93 + premix DFT tile (WGs 0..127) on f32 MFMA 16x16x4 instead of serialised LDS/VALU loop
# speedup vs baseline: 1.0069x; 1.0058x over previous
.LBB0_302:
	s_or_b64 exec, exec, s[28:29]
	v_readlane_b32 s0, v253, 29
	v_readlane_b32 s1, v253, 30
	v_mov_b32_e32 v0, v179
	s_andn2_b64 vcc, exec, s[0:1]
	s_waitcnt vmcnt(0) lgkmcnt(0)
	s_barrier
	s_cbranch_vccnz .LBB0_321
	v_ashrrev_i32_e32 v23, 4, v0
	v_readlane_b32 s0, v253, 44
	v_lshlrev_b32_e32 v1, 2, v0
	v_and_b32_e32 v4, 60, v1
	v_add_u32_e32 v2, s0, v23
	v_ashrrev_i32_e32 v3, 31, v2
	v_readlane_b32 s0, v253, 45
	v_lshlrev_b64 v[2:3], 13, v[2:3]
	v_readlane_b32 s1, v253, 46
	v_lshlrev_b32_e32 v176, 2, v4
	v_ashrrev_i32_e32 v31, 3, v0
	v_lshl_add_u64 v[2:3], s[0:1], 0, v[2:3]
	v_lshl_add_u64 v[2:3], v[2:3], 0, v[176:177]
	v_add_co_u32_e32 v6, vcc, 0x40000, v2
	s_movk_i32 s0, 0x104
	s_nop 0
	v_addc_co_u32_e32 v7, vcc, 0, v3, vcc
	global_load_dwordx4 v[8:11], v[2:3], off
	global_load_dwordx4 v[12:15], v[6:7], off
	v_lshlrev_b32_e32 v0, 3, v0
	v_mul_lo_u32 v1, v23, s0
	v_and_b32_e32 v0, 56, v0
	v_add3_u32 v30, 0, v1, v176
	v_lshl_add_u32 v1, v31, 2, 0
	v_xor_b32_e32 v32, 32, v31
	v_mul_u32_u24_e32 v2, 0x104, v0
	v_cmp_lt_i32_e64 s[38:39], 32, v31
	v_mad_u32_u24 v33, v0, s0, 0
	v_lshlrev_b32_e32 v34, 1, v32
	v_lshlrev_b32_e32 v35, 1, v31
	v_lshlrev_b32_e32 v16, 2, v4
	v_add_u32_e32 v36, v1, v2
	v_lshlrev_b32_e32 v176, 1, v0
	s_mov_b32 s3, s96
	s_branch .LBB0_306
.LBB0_305:
	s_waitcnt lgkmcnt(3)
	v_cvt_pk_bf16_f32 v0, v0, v1
	s_waitcnt lgkmcnt(2)
	v_mov_b32_e32 v1, v2
	s_ashr_i32 s6, s3, 31
	v_mov_b32_e32 v2, v3
	s_lshr_b32 s6, s6, 28
	v_cvt_pk_bf16_f32 v1, v1, v2
	s_waitcnt lgkmcnt(1)
	s_add_i32 s7, s3, s6
	v_mov_b32_e32 v2, v4
	s_and_b32 s6, s7, 0x3fffff0
	v_mov_b32_e32 v3, v5
	s_sub_i32 s3, s3, s6
	v_cvt_pk_bf16_f32 v2, v2, v3
	s_waitcnt lgkmcnt(0)
	s_lshl_b32 s6, s3, 6
	s_lshl_b32 s3, s7, 2
	v_mov_b32_e32 v3, v6
	s_andn2_b32 s3, s3, 63
	v_mov_b32_e32 v4, v7
	v_cvt_pk_bf16_f32 v3, v3, v4
	v_add_u32_e32 v4, s3, v31
	v_ashrrev_i32_e32 v5, 31, v4
	v_readlane_b32 s20, v254, 15
	v_lshlrev_b64 v[4:5], 11, v[4:5]
	v_readlane_b32 s21, v254, 16
	s_ashr_i32 s7, s6, 31
	s_andn2_b64 vcc, exec, s[0:1]
	v_lshl_add_u64 v[4:5], s[20:21], 0, v[4:5]
	v_lshl_add_u64 v[4:5], s[6:7], 1, v[4:5]
	v_lshl_add_u64 v[4:5], v[4:5], 0, v[176:177]
	s_mov_b32 s3, s2
	global_store_dwordx4 v[4:5], v[0:3], off sc1
	s_cbranch_vccz .LBB0_321

.LBB0_311:
	v_lshrrev_b32_e32 v42, 6, v179
	v_and_b32_e32 v40, 15, v225
	v_lshrrev_b32_e32 v41, 4, v225
	v_readfirstlane_b32 s6, v42
	v_mul_u32_u24_e32 v54, 0x104, v40
	v_bfrev_b32_e32 v50, 1
	s_lshr_b32 s7, s6, 1
	s_and_b32 s6, s6, 1
	s_lshl_b32 s20, s7, 4
	s_mul_i32 s21, s6, 0x2080
	s_lshl_b32 s28, s6, 6
	v_add_u32_e32 v43, s20, v40
	v_lshl_add_u32 v54, v41, 2, v54
	v_cmp_lt_u32_e32 vcc, 32, v43
	v_add_u32_e32 v45, -32, v43
	v_mov_b32_e32 v47, 0x4100
	v_mov_b32_e32 v48, 0x4200
	v_add_u32_e32 v54, s21, v54
	v_cndmask_b32_e32 v44, v43, v45, vcc
	v_cndmask_b32_e32 v46, v47, v48, vcc
	v_cndmask_b32_e32 v49, 0, v50, vcc
	v_mul_u32_u24_e32 v51, v41, v44
	v_lshlrev_b32_e32 v52, 2, v44
	v_xor_b32_e32 v55, s4, v49
	ds_read_b32 v80, v54 offset:0
	ds_read_b32 v81, v54 offset:16
	ds_read_b32 v82, v54 offset:32
	ds_read_b32 v83, v54 offset:48
	ds_read_b32 v84, v54 offset:64
	ds_read_b32 v85, v54 offset:80
	ds_read_b32 v86, v54 offset:96
	ds_read_b32 v87, v54 offset:112
	ds_read_b32 v88, v54 offset:128
	ds_read_b32 v89, v54 offset:144
	ds_read_b32 v90, v54 offset:160
	ds_read_b32 v91, v54 offset:176
	ds_read_b32 v92, v54 offset:192
	ds_read_b32 v93, v54 offset:208
	ds_read_b32 v94, v54 offset:224
	ds_read_b32 v95, v54 offset:240
	v_mad_u32_u24 v53, v52, 0, v51
	v_and_b32_e32 v53, 63, v53
	v_lshl_add_u32 v53, v53, 2, v46
	ds_read_b32 v64, v53
	v_mad_u32_u24 v53, v52, 1, v51
	v_and_b32_e32 v53, 63, v53
	v_lshl_add_u32 v53, v53, 2, v46
	ds_read_b32 v65, v53
	v_mad_u32_u24 v53, v52, 2, v51
	v_and_b32_e32 v53, 63, v53
	v_lshl_add_u32 v53, v53, 2, v46
	ds_read_b32 v66, v53
	v_mad_u32_u24 v53, v52, 3, v51
	v_and_b32_e32 v53, 63, v53
	v_lshl_add_u32 v53, v53, 2, v46
	ds_read_b32 v67, v53
	v_mad_u32_u24 v53, v52, 4, v51
	v_and_b32_e32 v53, 63, v53
	v_lshl_add_u32 v53, v53, 2, v46
	ds_read_b32 v68, v53
	v_mad_u32_u24 v53, v52, 5, v51
	v_and_b32_e32 v53, 63, v53
	v_lshl_add_u32 v53, v53, 2, v46
	ds_read_b32 v69, v53
	v_mad_u32_u24 v53, v52, 6, v51
	v_and_b32_e32 v53, 63, v53
	v_lshl_add_u32 v53, v53, 2, v46
	ds_read_b32 v70, v53
	v_mad_u32_u24 v53, v52, 7, v51
	v_and_b32_e32 v53, 63, v53
	v_lshl_add_u32 v53, v53, 2, v46
	ds_read_b32 v71, v53
	v_mad_u32_u24 v53, v52, 8, v51
	v_and_b32_e32 v53, 63, v53
	v_lshl_add_u32 v53, v53, 2, v46
	ds_read_b32 v72, v53
	v_mad_u32_u24 v53, v52, 9, v51
	v_and_b32_e32 v53, 63, v53
	v_lshl_add_u32 v53, v53, 2, v46
	ds_read_b32 v73, v53
	v_mad_u32_u24 v53, v52, 10, v51
	v_and_b32_e32 v53, 63, v53
	v_lshl_add_u32 v53, v53, 2, v46
	ds_read_b32 v74, v53
	v_mad_u32_u24 v53, v52, 11, v51
	v_and_b32_e32 v53, 63, v53
	v_lshl_add_u32 v53, v53, 2, v46
	ds_read_b32 v75, v53
	v_mad_u32_u24 v53, v52, 12, v51
	v_and_b32_e32 v53, 63, v53
	v_lshl_add_u32 v53, v53, 2, v46
	ds_read_b32 v76, v53
	v_mad_u32_u24 v53, v52, 13, v51
	v_and_b32_e32 v53, 63, v53
	v_lshl_add_u32 v53, v53, 2, v46
	ds_read_b32 v77, v53
	v_mad_u32_u24 v53, v52, 14, v51
	v_and_b32_e32 v53, 63, v53
	v_lshl_add_u32 v53, v53, 2, v46
	ds_read_b32 v78, v53
	v_mad_u32_u24 v53, v52, 15, v51
	v_and_b32_e32 v53, 63, v53
	v_lshl_add_u32 v53, v53, 2, v46
	ds_read_b32 v79, v53
	ds_read_b32 v96, v54 offset:4160
	ds_read_b32 v97, v54 offset:4176
	ds_read_b32 v98, v54 offset:4192
	ds_read_b32 v99, v54 offset:4208
	ds_read_b32 v100, v54 offset:4224
	ds_read_b32 v101, v54 offset:4240
	ds_read_b32 v102, v54 offset:4256
	ds_read_b32 v103, v54 offset:4272
	ds_read_b32 v104, v54 offset:4288
	ds_read_b32 v105, v54 offset:4304
	ds_read_b32 v106, v54 offset:4320
	ds_read_b32 v107, v54 offset:4336
	ds_read_b32 v108, v54 offset:4352
	ds_read_b32 v109, v54 offset:4368
	ds_read_b32 v110, v54 offset:4384
	ds_read_b32 v111, v54 offset:4400
	v_lshlrev_b32_e32 v112, 11, v43
	v_readlane_b32 s20, v254, 15
	v_readlane_b32 s21, v254, 16
	v_lshl_add_u32 v112, v41, 3, v112
	s_lshr_b32 s6, s3, 4
	s_and_b32 s7, s3, 15
	s_lshl_b32 s6, s6, 17
	s_lshl_b32 s7, s7, 7
	v_add_u32_e32 v112, s28, v112
	s_add_i32 s6, s6, s7
	s_add_u32 s20, s20, s6
	s_addc_u32 s21, s21, 0
	s_waitcnt lgkmcnt(0)
	v_mfma_f32_16x16x4_f32 v[56:59], v80, v64, 0
	v_mfma_f32_16x16x4_f32 v[60:63], v96, v64, 0
	v_mfma_f32_16x16x4_f32 v[56:59], v81, v65, v[56:59]
	v_mfma_f32_16x16x4_f32 v[60:63], v97, v65, v[60:63]
	v_mfma_f32_16x16x4_f32 v[56:59], v82, v66, v[56:59]
	v_mfma_f32_16x16x4_f32 v[60:63], v98, v66, v[60:63]
	v_mfma_f32_16x16x4_f32 v[56:59], v83, v67, v[56:59]
	v_mfma_f32_16x16x4_f32 v[60:63], v99, v67, v[60:63]
	v_mfma_f32_16x16x4_f32 v[56:59], v84, v68, v[56:59]
	v_mfma_f32_16x16x4_f32 v[60:63], v100, v68, v[60:63]
	v_mfma_f32_16x16x4_f32 v[56:59], v85, v69, v[56:59]
	v_mfma_f32_16x16x4_f32 v[60:63], v101, v69, v[60:63]
	v_mfma_f32_16x16x4_f32 v[56:59], v86, v70, v[56:59]
	v_mfma_f32_16x16x4_f32 v[60:63], v102, v70, v[60:63]
	v_mfma_f32_16x16x4_f32 v[56:59], v87, v71, v[56:59]
	v_mfma_f32_16x16x4_f32 v[60:63], v103, v71, v[60:63]
	v_mfma_f32_16x16x4_f32 v[56:59], v88, v72, v[56:59]
	v_mfma_f32_16x16x4_f32 v[60:63], v104, v72, v[60:63]
	v_mfma_f32_16x16x4_f32 v[56:59], v89, v73, v[56:59]
	v_mfma_f32_16x16x4_f32 v[60:63], v105, v73, v[60:63]
	v_mfma_f32_16x16x4_f32 v[56:59], v90, v74, v[56:59]
	v_mfma_f32_16x16x4_f32 v[60:63], v106, v74, v[60:63]
	v_mfma_f32_16x16x4_f32 v[56:59], v91, v75, v[56:59]
	v_mfma_f32_16x16x4_f32 v[60:63], v107, v75, v[60:63]
	v_mfma_f32_16x16x4_f32 v[56:59], v92, v76, v[56:59]
	v_mfma_f32_16x16x4_f32 v[60:63], v108, v76, v[60:63]
	v_mfma_f32_16x16x4_f32 v[56:59], v93, v77, v[56:59]
	v_mfma_f32_16x16x4_f32 v[60:63], v109, v77, v[60:63]
	v_mfma_f32_16x16x4_f32 v[56:59], v94, v78, v[56:59]
	v_mfma_f32_16x16x4_f32 v[60:63], v110, v78, v[60:63]
	v_mfma_f32_16x16x4_f32 v[56:59], v95, v79, v[56:59]
	v_mfma_f32_16x16x4_f32 v[60:63], v111, v79, v[60:63]
	s_andn2_b64 vcc, exec, s[0:1]
	s_mov_b32 s3, s2
	s_nop 15
	s_nop 7
	v_mul_f32_e32 v56, v55, v56
	v_mul_f32_e32 v57, v55, v57
	v_mul_f32_e32 v58, v55, v58
	v_mul_f32_e32 v59, v55, v59
	v_mul_f32_e32 v60, v55, v60
	v_mul_f32_e32 v61, v55, v61
	v_mul_f32_e32 v62, v55, v62
	v_mul_f32_e32 v63, v55, v63
	v_cvt_pk_bf16_f32 v114, v56, v57
	v_cvt_pk_bf16_f32 v115, v58, v59
	v_cvt_pk_bf16_f32 v116, v60, v61
	v_cvt_pk_bf16_f32 v117, v62, v63
	global_store_dwordx2 v112, v[114:115], s[20:21] sc1
	global_store_dwordx2 v112, v[116:117], s[20:21] offset:32 sc1
	s_cbranch_vccz .LBB0_321
	s_branch .LBB0_306
